# dense attention softmax: v_exp interleaved with fma/add/cvt (trans/plain VALU overlap), same sum order
# baseline (speedup 1.0000x reference)
; __device__ __forceinline__ void partialSM(f32x16& p0, f32x16& p1, float& m_reg, float& mn, float& alpha) {
;     ...
;   float mnC = -mn * C;
; #pragma unroll
;   for (int r = 0; r < 16; ++r) p0[r] = fmaf(p0[r], C, mnC);
; #pragma unroll
;   for (int r = 0; r < 16; ++r) p1[r] = fmaf(p1[r], C, mnC);
; #pragma unroll
;   for (int r = 0; r < 16; ++r) p0[r] = __builtin_amdgcn_exp2f(p0[r]);
; }
; __device__ __forceinline__ void finishSM(f32x16& p0, f32x16& p1, float alpha, float& l_reg, bf16x8& pa0, bf16x8& pa1, bf16x8& pa2, bf16x8& pa3) {
; #pragma unroll
;   for (int r = 0; r < 16; ++r) p1[r] = __builtin_amdgcn_exp2f(p1[r]);
;   float ps = 0;
; #pragma unroll
;   for (int r = 0; r < 16; ++r) ps += p0[r];
; #pragma unroll
;   for (int r = 0; r < 16; ++r) ps += p1[r];
;   { auto rr = __builtin_amdgcn_permlane32_swap(__float_as_uint(ps), __float_as_uint(ps), false, false);
;     ps = __uint_as_float(rr[0]) + __uint_as_float(rr[1]); }
;   l_reg = l_reg * alpha + ps;
;     ...
;   PK4(p0, 0, pa0); PK4(p0, 8, pa1); PK4(p1, 0, pa2); PK4(p1, 8, pa3);
.Lda_common_0:
.Lda_noresc_0:
	v_fma_f32 v80, v80, s92, v214
	v_fma_f32 v81, v81, s92, v214
	v_fma_f32 v82, v82, s92, v214
	v_exp_f32_e32 v80, v80
	v_fma_f32 v83, v83, s92, v214
	v_exp_f32_e32 v81, v81
	v_fma_f32 v84, v84, s92, v214
	v_exp_f32_e32 v82, v82
	v_fma_f32 v85, v85, s92, v214
	v_exp_f32_e32 v83, v83
	v_add_f32_e32 v190, v80, v81
	v_fma_f32 v86, v86, s92, v214
	v_exp_f32_e32 v84, v84
	v_cvt_pk_bf16_f32 v166, v80, v81
	v_fma_f32 v87, v87, s92, v214
	v_exp_f32_e32 v85, v85
	v_add_f32_e32 v191, v82, v83
	v_fma_f32 v88, v88, s92, v214
	v_exp_f32_e32 v86, v86
	v_add_f32_e32 v190, v190, v84
	v_cvt_pk_bf16_f32 v167, v82, v83
	v_fma_f32 v89, v89, s92, v214
	v_exp_f32_e32 v87, v87
	v_add_f32_e32 v191, v191, v85
	v_fma_f32 v90, v90, s92, v214
	v_exp_f32_e32 v88, v88
	v_add_f32_e32 v190, v190, v86
	v_cvt_pk_bf16_f32 v168, v84, v85
	v_fma_f32 v91, v91, s92, v214
	v_exp_f32_e32 v89, v89
	v_add_f32_e32 v191, v191, v87
	v_fma_f32 v92, v92, s92, v214
	v_exp_f32_e32 v90, v90
	v_add_f32_e32 v190, v190, v88
	v_cvt_pk_bf16_f32 v169, v86, v87
	v_fma_f32 v93, v93, s92, v214
	v_exp_f32_e32 v91, v91
	v_add_f32_e32 v191, v191, v89
	v_fma_f32 v94, v94, s92, v214
	v_exp_f32_e32 v92, v92
	v_add_f32_e32 v190, v190, v90
	v_cvt_pk_bf16_f32 v170, v88, v89
	v_fma_f32 v95, v95, s92, v214
	v_exp_f32_e32 v93, v93
	v_add_f32_e32 v191, v191, v91
	v_fma_f32 v64, v64, s92, v214
	v_exp_f32_e32 v94, v94
	v_add_f32_e32 v190, v190, v92
	v_cvt_pk_bf16_f32 v171, v90, v91
	v_fma_f32 v65, v65, s92, v214
	v_exp_f32_e32 v95, v95
	v_add_f32_e32 v191, v191, v93
	v_fma_f32 v66, v66, s92, v214
	v_exp_f32_e32 v64, v64
	v_add_f32_e32 v190, v190, v94
	v_cvt_pk_bf16_f32 v172, v92, v93
	v_fma_f32 v67, v67, s92, v214
	v_exp_f32_e32 v65, v65
	v_add_f32_e32 v191, v191, v95
	v_fma_f32 v68, v68, s92, v214
	v_exp_f32_e32 v66, v66
	v_add_f32_e32 v190, v190, v64
	v_cvt_pk_bf16_f32 v173, v94, v95
	v_fma_f32 v69, v69, s92, v214
	v_exp_f32_e32 v67, v67
	v_add_f32_e32 v191, v191, v65
	v_fma_f32 v70, v70, s92, v214
	v_exp_f32_e32 v68, v68
	v_add_f32_e32 v190, v190, v66
	v_cvt_pk_bf16_f32 v176, v64, v65
	v_fma_f32 v71, v71, s92, v214
	v_exp_f32_e32 v69, v69
	v_add_f32_e32 v191, v191, v67
	v_fma_f32 v72, v72, s92, v214
	v_exp_f32_e32 v70, v70
	v_add_f32_e32 v190, v190, v68
	v_cvt_pk_bf16_f32 v177, v66, v67
	v_fma_f32 v73, v73, s92, v214
	v_exp_f32_e32 v71, v71
	v_add_f32_e32 v191, v191, v69
	v_fma_f32 v74, v74, s92, v214
	v_exp_f32_e32 v72, v72
	v_add_f32_e32 v190, v190, v70
	v_cvt_pk_bf16_f32 v178, v68, v69
	v_fma_f32 v75, v75, s92, v214
	v_exp_f32_e32 v73, v73
	v_add_f32_e32 v191, v191, v71
	v_fma_f32 v76, v76, s92, v214
	v_exp_f32_e32 v74, v74
	v_add_f32_e32 v190, v190, v72
	v_cvt_pk_bf16_f32 v179, v70, v71
	v_fma_f32 v77, v77, s92, v214
	v_exp_f32_e32 v75, v75
	v_add_f32_e32 v191, v191, v73
	v_fma_f32 v78, v78, s92, v214
	v_exp_f32_e32 v76, v76
	v_add_f32_e32 v190, v190, v74
	v_cvt_pk_bf16_f32 v180, v72, v73
	v_fma_f32 v79, v79, s92, v214
	v_exp_f32_e32 v77, v77
	v_add_f32_e32 v191, v191, v75
	v_exp_f32_e32 v78, v78
	v_add_f32_e32 v190, v190, v76
	v_cvt_pk_bf16_f32 v181, v74, v75
	v_exp_f32_e32 v79, v79
	v_add_f32_e32 v191, v191, v77
	v_add_f32_e32 v190, v190, v78
	v_cvt_pk_bf16_f32 v182, v76, v77
	v_add_f32_e32 v191, v191, v79
	v_cvt_pk_bf16_f32 v183, v78, v79
	v_add_f32_e32 v190, v190, v191
	v_permlane32_swap_b32_e32 v166, v168
	v_permlane32_swap_b32_e32 v167, v169
	v_permlane32_swap_b32_e32 v170, v172
	v_permlane32_swap_b32_e32 v171, v173
	v_permlane32_swap_b32_e32 v176, v178
	v_permlane32_swap_b32_e32 v177, v179
	v_permlane32_swap_b32_e32 v180, v182
	v_permlane32_swap_b32_e32 v181, v183
	v_add_f32_e32 v175, v175, v190
	s_add_u32 s31, s31, 1
	s_cmp_lt_u32 s31, 132
	s_cbranch_scc0 .Lda_skipk_0
	ds_read_b128 v[150:153], v204 offset:16384
	ds_read_b128 v[154:157], v204 offset:24576
	ds_read_b128 v[158:161], v205 offset:16384
	ds_read_b128 v[162:165], v205 offset:24576
	ds_read_b128 v[228:231], v206 offset:16384
	ds_read_b128 v[232:235], v206 offset:24576
	ds_read_b128 v[236:239], v207 offset:16384
	ds_read_b128 v[240:243], v207 offset:24576

; __device__ __forceinline__ void partialSM(f32x16& p0, f32x16& p1, float& m_reg, float& mn, float& alpha) {
;     ...
;   float mnC = -mn * C;
; #pragma unroll
;   for (int r = 0; r < 16; ++r) p0[r] = fmaf(p0[r], C, mnC);
; #pragma unroll
;   for (int r = 0; r < 16; ++r) p1[r] = fmaf(p1[r], C, mnC);
; #pragma unroll
;   for (int r = 0; r < 16; ++r) p0[r] = __builtin_amdgcn_exp2f(p0[r]);
; }
; __device__ __forceinline__ void finishSM(f32x16& p0, f32x16& p1, float alpha, float& l_reg, bf16x8& pa0, bf16x8& pa1, bf16x8& pa2, bf16x8& pa3) {
; #pragma unroll
;   for (int r = 0; r < 16; ++r) p1[r] = __builtin_amdgcn_exp2f(p1[r]);
;   float ps = 0;
; #pragma unroll
;   for (int r = 0; r < 16; ++r) ps += p0[r];
; #pragma unroll
;   for (int r = 0; r < 16; ++r) ps += p1[r];
;   { auto rr = __builtin_amdgcn_permlane32_swap(__float_as_uint(ps), __float_as_uint(ps), false, false);
;     ps = __uint_as_float(rr[0]) + __uint_as_float(rr[1]); }
;   l_reg = l_reg * alpha + ps;
;     ...
;   PK4(p0, 0, pa0); PK4(p0, 8, pa1); PK4(p1, 0, pa2); PK4(p1, 8, pa3);
.Lda_common_1:
.Lda_noresc_1:
	v_fma_f32 v80, v80, s92, v214
	v_fma_f32 v81, v81, s92, v214
	v_fma_f32 v82, v82, s92, v214
	v_exp_f32_e32 v80, v80
	v_fma_f32 v83, v83, s92, v214
	v_exp_f32_e32 v81, v81
	v_fma_f32 v84, v84, s92, v214
	v_exp_f32_e32 v82, v82
	v_fma_f32 v85, v85, s92, v214
	v_exp_f32_e32 v83, v83
	v_add_f32_e32 v190, v80, v81
	v_fma_f32 v86, v86, s92, v214
	v_exp_f32_e32 v84, v84
	v_cvt_pk_bf16_f32 v166, v80, v81
	v_fma_f32 v87, v87, s92, v214
	v_exp_f32_e32 v85, v85
	v_add_f32_e32 v191, v82, v83
	v_fma_f32 v88, v88, s92, v214
	v_exp_f32_e32 v86, v86
	v_add_f32_e32 v190, v190, v84
	v_cvt_pk_bf16_f32 v167, v82, v83
	v_fma_f32 v89, v89, s92, v214
	v_exp_f32_e32 v87, v87
	v_add_f32_e32 v191, v191, v85
	v_fma_f32 v90, v90, s92, v214
	v_exp_f32_e32 v88, v88
	v_add_f32_e32 v190, v190, v86
	v_cvt_pk_bf16_f32 v168, v84, v85
	v_fma_f32 v91, v91, s92, v214
	v_exp_f32_e32 v89, v89
	v_add_f32_e32 v191, v191, v87
	v_fma_f32 v92, v92, s92, v214
	v_exp_f32_e32 v90, v90
	v_add_f32_e32 v190, v190, v88
	v_cvt_pk_bf16_f32 v169, v86, v87
	v_fma_f32 v93, v93, s92, v214
	v_exp_f32_e32 v91, v91
	v_add_f32_e32 v191, v191, v89
	v_fma_f32 v94, v94, s92, v214
	v_exp_f32_e32 v92, v92
	v_add_f32_e32 v190, v190, v90
	v_cvt_pk_bf16_f32 v170, v88, v89
	v_fma_f32 v95, v95, s92, v214
	v_exp_f32_e32 v93, v93
	v_add_f32_e32 v191, v191, v91
	v_fma_f32 v64, v64, s92, v214
	v_exp_f32_e32 v94, v94
	v_add_f32_e32 v190, v190, v92
	v_cvt_pk_bf16_f32 v171, v90, v91
	v_fma_f32 v65, v65, s92, v214
	v_exp_f32_e32 v95, v95
	v_add_f32_e32 v191, v191, v93
	v_fma_f32 v66, v66, s92, v214
	v_exp_f32_e32 v64, v64
	v_add_f32_e32 v190, v190, v94
	v_cvt_pk_bf16_f32 v172, v92, v93
	v_fma_f32 v67, v67, s92, v214
	v_exp_f32_e32 v65, v65
	v_add_f32_e32 v191, v191, v95
	v_fma_f32 v68, v68, s92, v214
	v_exp_f32_e32 v66, v66
	v_add_f32_e32 v190, v190, v64
	v_cvt_pk_bf16_f32 v173, v94, v95
	v_fma_f32 v69, v69, s92, v214
	v_exp_f32_e32 v67, v67
	v_add_f32_e32 v191, v191, v65
	v_fma_f32 v70, v70, s92, v214
	v_exp_f32_e32 v68, v68
	v_add_f32_e32 v190, v190, v66
	v_cvt_pk_bf16_f32 v176, v64, v65
	v_fma_f32 v71, v71, s92, v214
	v_exp_f32_e32 v69, v69
	v_add_f32_e32 v191, v191, v67
	v_fma_f32 v72, v72, s92, v214
	v_exp_f32_e32 v70, v70
	v_add_f32_e32 v190, v190, v68
	v_cvt_pk_bf16_f32 v177, v66, v67
	v_fma_f32 v73, v73, s92, v214
	v_exp_f32_e32 v71, v71
	v_add_f32_e32 v191, v191, v69
	v_fma_f32 v74, v74, s92, v214
	v_exp_f32_e32 v72, v72
	v_add_f32_e32 v190, v190, v70
	v_cvt_pk_bf16_f32 v178, v68, v69
	v_fma_f32 v75, v75, s92, v214
	v_exp_f32_e32 v73, v73
	v_add_f32_e32 v191, v191, v71
	v_fma_f32 v76, v76, s92, v214
	v_exp_f32_e32 v74, v74
	v_add_f32_e32 v190, v190, v72
	v_cvt_pk_bf16_f32 v179, v70, v71
	v_fma_f32 v77, v77, s92, v214
	v_exp_f32_e32 v75, v75
	v_add_f32_e32 v191, v191, v73
	v_fma_f32 v78, v78, s92, v214
	v_exp_f32_e32 v76, v76
	v_add_f32_e32 v190, v190, v74
	v_cvt_pk_bf16_f32 v180, v72, v73
	v_fma_f32 v79, v79, s92, v214
	v_exp_f32_e32 v77, v77
	v_add_f32_e32 v191, v191, v75
	v_exp_f32_e32 v78, v78
	v_add_f32_e32 v190, v190, v76
	v_cvt_pk_bf16_f32 v181, v74, v75
	v_exp_f32_e32 v79, v79
	v_add_f32_e32 v191, v191, v77
	v_add_f32_e32 v190, v190, v78
	v_cvt_pk_bf16_f32 v182, v76, v77
	v_add_f32_e32 v191, v191, v79
	v_cvt_pk_bf16_f32 v183, v78, v79
	v_add_f32_e32 v190, v190, v191
	v_permlane32_swap_b32_e32 v166, v168
	v_permlane32_swap_b32_e32 v167, v169
	v_permlane32_swap_b32_e32 v170, v172
	v_permlane32_swap_b32_e32 v171, v173
	v_permlane32_swap_b32_e32 v176, v178
	v_permlane32_swap_b32_e32 v177, v179
	v_permlane32_swap_b32_e32 v180, v182
	v_permlane32_swap_b32_e32 v181, v183
	v_add_f32_e32 v175, v175, v190
	s_add_u32 s31, s31, 1
	s_cmp_lt_u32 s31, 132
	s_cbranch_scc0 .Lda_skipk_1
	ds_read_b128 v[150:153], v204 offset:32768
	ds_read_b128 v[154:157], v204 offset:40960
	ds_read_b128 v[158:161], v205 offset:32768
	ds_read_b128 v[162:165], v205 offset:40960
	ds_read_b128 v[228:231], v206 offset:32768
	ds_read_b128 v[232:235], v206 offset:40960
	ds_read_b128 v[236:239], v207 offset:32768
	ds_read_b128 v[240:243], v207 offset:40960

; __device__ __forceinline__ void partialSM(f32x16& p0, f32x16& p1, float& m_reg, float& mn, float& alpha) {
;     ...
;   float mnC = -mn * C;
; #pragma unroll
;   for (int r = 0; r < 16; ++r) p0[r] = fmaf(p0[r], C, mnC);
; #pragma unroll
;   for (int r = 0; r < 16; ++r) p1[r] = fmaf(p1[r], C, mnC);
; #pragma unroll
;   for (int r = 0; r < 16; ++r) p0[r] = __builtin_amdgcn_exp2f(p0[r]);
; }
; __device__ __forceinline__ void finishSM(f32x16& p0, f32x16& p1, float alpha, float& l_reg, bf16x8& pa0, bf16x8& pa1, bf16x8& pa2, bf16x8& pa3) {
; #pragma unroll
;   for (int r = 0; r < 16; ++r) p1[r] = __builtin_amdgcn_exp2f(p1[r]);
;   float ps = 0;
; #pragma unroll
;   for (int r = 0; r < 16; ++r) ps += p0[r];
; #pragma unroll
;   for (int r = 0; r < 16; ++r) ps += p1[r];
;   { auto rr = __builtin_amdgcn_permlane32_swap(__float_as_uint(ps), __float_as_uint(ps), false, false);
;     ps = __uint_as_float(rr[0]) + __uint_as_float(rr[1]); }
;   l_reg = l_reg * alpha + ps;
;     ...
;   PK4(p0, 0, pa0); PK4(p0, 8, pa1); PK4(p1, 0, pa2); PK4(p1, 8, pa3);
.Lda_common_2:
.Lda_noresc_2:
	v_fma_f32 v80, v80, s92, v214
	v_fma_f32 v81, v81, s92, v214
	v_fma_f32 v82, v82, s92, v214
	v_exp_f32_e32 v80, v80
	v_fma_f32 v83, v83, s92, v214
	v_exp_f32_e32 v81, v81
	v_fma_f32 v84, v84, s92, v214
	v_exp_f32_e32 v82, v82
	v_fma_f32 v85, v85, s92, v214
	v_exp_f32_e32 v83, v83
	v_add_f32_e32 v190, v80, v81
	v_fma_f32 v86, v86, s92, v214
	v_exp_f32_e32 v84, v84
	v_cvt_pk_bf16_f32 v166, v80, v81
	v_fma_f32 v87, v87, s92, v214
	v_exp_f32_e32 v85, v85
	v_add_f32_e32 v191, v82, v83
	v_fma_f32 v88, v88, s92, v214
	v_exp_f32_e32 v86, v86
	v_add_f32_e32 v190, v190, v84
	v_cvt_pk_bf16_f32 v167, v82, v83
	v_fma_f32 v89, v89, s92, v214
	v_exp_f32_e32 v87, v87
	v_add_f32_e32 v191, v191, v85
	v_fma_f32 v90, v90, s92, v214
	v_exp_f32_e32 v88, v88
	v_add_f32_e32 v190, v190, v86
	v_cvt_pk_bf16_f32 v168, v84, v85
	v_fma_f32 v91, v91, s92, v214
	v_exp_f32_e32 v89, v89
	v_add_f32_e32 v191, v191, v87
	v_fma_f32 v92, v92, s92, v214
	v_exp_f32_e32 v90, v90
	v_add_f32_e32 v190, v190, v88
	v_cvt_pk_bf16_f32 v169, v86, v87
	v_fma_f32 v93, v93, s92, v214
	v_exp_f32_e32 v91, v91
	v_add_f32_e32 v191, v191, v89
	v_fma_f32 v94, v94, s92, v214
	v_exp_f32_e32 v92, v92
	v_add_f32_e32 v190, v190, v90
	v_cvt_pk_bf16_f32 v170, v88, v89
	v_fma_f32 v95, v95, s92, v214
	v_exp_f32_e32 v93, v93
	v_add_f32_e32 v191, v191, v91
	v_fma_f32 v64, v64, s92, v214
	v_exp_f32_e32 v94, v94
	v_add_f32_e32 v190, v190, v92
	v_cvt_pk_bf16_f32 v171, v90, v91
	v_fma_f32 v65, v65, s92, v214
	v_exp_f32_e32 v95, v95
	v_add_f32_e32 v191, v191, v93
	v_fma_f32 v66, v66, s92, v214
	v_exp_f32_e32 v64, v64
	v_add_f32_e32 v190, v190, v94
	v_cvt_pk_bf16_f32 v172, v92, v93
	v_fma_f32 v67, v67, s92, v214
	v_exp_f32_e32 v65, v65
	v_add_f32_e32 v191, v191, v95
	v_fma_f32 v68, v68, s92, v214
	v_exp_f32_e32 v66, v66
	v_add_f32_e32 v190, v190, v64
	v_cvt_pk_bf16_f32 v173, v94, v95
	v_fma_f32 v69, v69, s92, v214
	v_exp_f32_e32 v67, v67
	v_add_f32_e32 v191, v191, v65
	v_fma_f32 v70, v70, s92, v214
	v_exp_f32_e32 v68, v68
	v_add_f32_e32 v190, v190, v66
	v_cvt_pk_bf16_f32 v176, v64, v65
	v_fma_f32 v71, v71, s92, v214
	v_exp_f32_e32 v69, v69
	v_add_f32_e32 v191, v191, v67
	v_fma_f32 v72, v72, s92, v214
	v_exp_f32_e32 v70, v70
	v_add_f32_e32 v190, v190, v68
	v_cvt_pk_bf16_f32 v177, v66, v67
	v_fma_f32 v73, v73, s92, v214
	v_exp_f32_e32 v71, v71
	v_add_f32_e32 v191, v191, v69
	v_fma_f32 v74, v74, s92, v214
	v_exp_f32_e32 v72, v72
	v_add_f32_e32 v190, v190, v70
	v_cvt_pk_bf16_f32 v178, v68, v69
	v_fma_f32 v75, v75, s92, v214
	v_exp_f32_e32 v73, v73
	v_add_f32_e32 v191, v191, v71
	v_fma_f32 v76, v76, s92, v214
	v_exp_f32_e32 v74, v74
	v_add_f32_e32 v190, v190, v72
	v_cvt_pk_bf16_f32 v179, v70, v71
	v_fma_f32 v77, v77, s92, v214
	v_exp_f32_e32 v75, v75
	v_add_f32_e32 v191, v191, v73
	v_fma_f32 v78, v78, s92, v214
	v_exp_f32_e32 v76, v76
	v_add_f32_e32 v190, v190, v74
	v_cvt_pk_bf16_f32 v180, v72, v73
	v_fma_f32 v79, v79, s92, v214
	v_exp_f32_e32 v77, v77
	v_add_f32_e32 v191, v191, v75
	v_exp_f32_e32 v78, v78
	v_add_f32_e32 v190, v190, v76
	v_cvt_pk_bf16_f32 v181, v74, v75
	v_exp_f32_e32 v79, v79
	v_add_f32_e32 v191, v191, v77
	v_add_f32_e32 v190, v190, v78
	v_cvt_pk_bf16_f32 v182, v76, v77
	v_add_f32_e32 v191, v191, v79
	v_cvt_pk_bf16_f32 v183, v78, v79
	v_add_f32_e32 v190, v190, v191
	v_permlane32_swap_b32_e32 v166, v168
	v_permlane32_swap_b32_e32 v167, v169
	v_permlane32_swap_b32_e32 v170, v172
	v_permlane32_swap_b32_e32 v171, v173
	v_permlane32_swap_b32_e32 v176, v178
	v_permlane32_swap_b32_e32 v177, v179
	v_permlane32_swap_b32_e32 v180, v182
	v_permlane32_swap_b32_e32 v181, v183
	v_add_f32_e32 v175, v175, v190
	s_add_u32 s31, s31, 1
	s_cmp_lt_u32 s31, 132
	s_cbranch_scc0 .Lda_skipk_2
	ds_read_b128 v[150:153], v204 offset:49152
	ds_read_b128 v[154:157], v204 offset:57344
	ds_read_b128 v[158:161], v205 offset:49152
	ds_read_b128 v[162:165], v205 offset:57344
	ds_read_b128 v[228:231], v206 offset:49152
	ds_read_b128 v[232:235], v206 offset:57344
	ds_read_b128 v[236:239], v207 offset:49152
	ds_read_b128 v[240:243], v207 offset:57344

; __device__ __forceinline__ void partialSM(f32x16& p0, f32x16& p1, float& m_reg, float& mn, float& alpha) {
;     ...
;   float mnC = -mn * C;
; #pragma unroll
;   for (int r = 0; r < 16; ++r) p0[r] = fmaf(p0[r], C, mnC);
; #pragma unroll
;   for (int r = 0; r < 16; ++r) p1[r] = fmaf(p1[r], C, mnC);
; #pragma unroll
;   for (int r = 0; r < 16; ++r) p0[r] = __builtin_amdgcn_exp2f(p0[r]);
; }
; __device__ __forceinline__ void finishSM(f32x16& p0, f32x16& p1, float alpha, float& l_reg, bf16x8& pa0, bf16x8& pa1, bf16x8& pa2, bf16x8& pa3) {
; #pragma unroll
;   for (int r = 0; r < 16; ++r) p1[r] = __builtin_amdgcn_exp2f(p1[r]);
;   float ps = 0;
; #pragma unroll
;   for (int r = 0; r < 16; ++r) ps += p0[r];
; #pragma unroll
;   for (int r = 0; r < 16; ++r) ps += p1[r];
;   { auto rr = __builtin_amdgcn_permlane32_swap(__float_as_uint(ps), __float_as_uint(ps), false, false);
;     ps = __uint_as_float(rr[0]) + __uint_as_float(rr[1]); }
;   l_reg = l_reg * alpha + ps;
;     ...
;   PK4(p0, 0, pa0); PK4(p0, 8, pa1); PK4(p1, 0, pa2); PK4(p1, 8, pa3);
.Lda_common_3:
.Lda_noresc_3:
	v_fma_f32 v80, v80, s92, v214
	v_fma_f32 v81, v81, s92, v214
	v_fma_f32 v82, v82, s92, v214
	v_exp_f32_e32 v80, v80
	v_fma_f32 v83, v83, s92, v214
	v_exp_f32_e32 v81, v81
	v_fma_f32 v84, v84, s92, v214
	v_exp_f32_e32 v82, v82
	v_fma_f32 v85, v85, s92, v214
	v_exp_f32_e32 v83, v83
	v_add_f32_e32 v190, v80, v81
	v_fma_f32 v86, v86, s92, v214
	v_exp_f32_e32 v84, v84
	v_cvt_pk_bf16_f32 v166, v80, v81
	v_fma_f32 v87, v87, s92, v214
	v_exp_f32_e32 v85, v85
	v_add_f32_e32 v191, v82, v83
	v_fma_f32 v88, v88, s92, v214
	v_exp_f32_e32 v86, v86
	v_add_f32_e32 v190, v190, v84
	v_cvt_pk_bf16_f32 v167, v82, v83
	v_fma_f32 v89, v89, s92, v214
	v_exp_f32_e32 v87, v87
	v_add_f32_e32 v191, v191, v85
	v_fma_f32 v90, v90, s92, v214
	v_exp_f32_e32 v88, v88
	v_add_f32_e32 v190, v190, v86
	v_cvt_pk_bf16_f32 v168, v84, v85
	v_fma_f32 v91, v91, s92, v214
	v_exp_f32_e32 v89, v89
	v_add_f32_e32 v191, v191, v87
	v_fma_f32 v92, v92, s92, v214
	v_exp_f32_e32 v90, v90
	v_add_f32_e32 v190, v190, v88
	v_cvt_pk_bf16_f32 v169, v86, v87
	v_fma_f32 v93, v93, s92, v214
	v_exp_f32_e32 v91, v91
	v_add_f32_e32 v191, v191, v89
	v_fma_f32 v94, v94, s92, v214
	v_exp_f32_e32 v92, v92
	v_add_f32_e32 v190, v190, v90
	v_cvt_pk_bf16_f32 v170, v88, v89
	v_fma_f32 v95, v95, s92, v214
	v_exp_f32_e32 v93, v93
	v_add_f32_e32 v191, v191, v91
	v_fma_f32 v64, v64, s92, v214
	v_exp_f32_e32 v94, v94
	v_add_f32_e32 v190, v190, v92
	v_cvt_pk_bf16_f32 v171, v90, v91
	v_fma_f32 v65, v65, s92, v214
	v_exp_f32_e32 v95, v95
	v_add_f32_e32 v191, v191, v93
	v_fma_f32 v66, v66, s92, v214
	v_exp_f32_e32 v64, v64
	v_add_f32_e32 v190, v190, v94
	v_cvt_pk_bf16_f32 v172, v92, v93
	v_fma_f32 v67, v67, s92, v214
	v_exp_f32_e32 v65, v65
	v_add_f32_e32 v191, v191, v95
	v_fma_f32 v68, v68, s92, v214
	v_exp_f32_e32 v66, v66
	v_add_f32_e32 v190, v190, v64
	v_cvt_pk_bf16_f32 v173, v94, v95
	v_fma_f32 v69, v69, s92, v214
	v_exp_f32_e32 v67, v67
	v_add_f32_e32 v191, v191, v65
	v_fma_f32 v70, v70, s92, v214
	v_exp_f32_e32 v68, v68
	v_add_f32_e32 v190, v190, v66
	v_cvt_pk_bf16_f32 v176, v64, v65
	v_fma_f32 v71, v71, s92, v214
	v_exp_f32_e32 v69, v69
	v_add_f32_e32 v191, v191, v67
	v_fma_f32 v72, v72, s92, v214
	v_exp_f32_e32 v70, v70
	v_add_f32_e32 v190, v190, v68
	v_cvt_pk_bf16_f32 v177, v66, v67
	v_fma_f32 v73, v73, s92, v214
	v_exp_f32_e32 v71, v71
	v_add_f32_e32 v191, v191, v69
	v_fma_f32 v74, v74, s92, v214
	v_exp_f32_e32 v72, v72
	v_add_f32_e32 v190, v190, v70
	v_cvt_pk_bf16_f32 v178, v68, v69
	v_fma_f32 v75, v75, s92, v214
	v_exp_f32_e32 v73, v73
	v_add_f32_e32 v191, v191, v71
	v_fma_f32 v76, v76, s92, v214
	v_exp_f32_e32 v74, v74
	v_add_f32_e32 v190, v190, v72
	v_cvt_pk_bf16_f32 v179, v70, v71
	v_fma_f32 v77, v77, s92, v214
	v_exp_f32_e32 v75, v75
	v_add_f32_e32 v191, v191, v73
	v_fma_f32 v78, v78, s92, v214
	v_exp_f32_e32 v76, v76
	v_add_f32_e32 v190, v190, v74
	v_cvt_pk_bf16_f32 v180, v72, v73
	v_fma_f32 v79, v79, s92, v214
	v_exp_f32_e32 v77, v77
	v_add_f32_e32 v191, v191, v75
	v_exp_f32_e32 v78, v78
	v_add_f32_e32 v190, v190, v76
	v_cvt_pk_bf16_f32 v181, v74, v75
	v_exp_f32_e32 v79, v79
	v_add_f32_e32 v191, v191, v77
	v_add_f32_e32 v190, v190, v78
	v_cvt_pk_bf16_f32 v182, v76, v77
	v_add_f32_e32 v191, v191, v79
	v_cvt_pk_bf16_f32 v183, v78, v79
	v_add_f32_e32 v190, v190, v191
	v_permlane32_swap_b32_e32 v166, v168
	v_permlane32_swap_b32_e32 v167, v169
	v_permlane32_swap_b32_e32 v170, v172
	v_permlane32_swap_b32_e32 v171, v173
	v_permlane32_swap_b32_e32 v176, v178
	v_permlane32_swap_b32_e32 v177, v179
	v_permlane32_swap_b32_e32 v180, v182
	v_permlane32_swap_b32_e32 v181, v183
	v_add_f32_e32 v175, v175, v190
	s_add_u32 s31, s31, 1
	s_cmp_lt_u32 s31, 132
	s_cbranch_scc0 .Lda_skipk_3
	ds_read_b128 v[150:153], v204 offset:0
	ds_read_b128 v[154:157], v204 offset:8192
	ds_read_b128 v[158:161], v205 offset:0
	ds_read_b128 v[162:165], v205 offset:8192
	ds_read_b128 v[228:231], v206 offset:0
	ds_read_b128 v[232:235], v206 offset:8192
	ds_read_b128 v[236:239], v207 offset:0
	ds_read_b128 v[240:243], v207 offset:8192
